# phase 13 expert GEMM2 epilogue de-serialised: the 4 dependent (list entry -> routing weight) load pairs of a tile issued together before the row blocks
# speedup vs baseline: 1.0187x; 1.0187x over previous
.LBB0_959:
	s_nop 0
	global_load_dwordx4 v[0:3], v93, s[64:65] offset:48
	global_load_dwordx4 v[4:7], v93, s[64:65] offset:32
	global_load_dwordx4 v[8:11], v93, s[64:65] offset:16
	global_load_dwordx4 v[12:15], v93, s[64:65]
	s_ashr_i32 s74, s62, 4
	s_cmp_gt_i32 s74, -1
	s_cselect_b64 s[0:1], -1, 0
	s_mov_b64 s[66:67], 0x18080
	s_waitcnt vmcnt(1)
	v_readfirstlane_b32 s96, v8
	s_waitcnt vmcnt(0)
	v_readfirstlane_b32 s97, v15
	v_readfirstlane_b32 s56, v14
	v_readfirstlane_b32 s57, v13
	v_readfirstlane_b32 s80, v12
	global_load_dwordx4 v[12:15], v93, s[68:69] offset:48
	global_load_dwordx4 v[16:19], v93, s[68:69] offset:32
	global_load_dwordx4 v[20:23], v93, s[68:69] offset:16
	global_load_dwordx4 v[24:27], v93, s[68:69]
	s_add_i32 s2, s80, 0x7f
	s_add_i32 s3, s57, 0x7f
	s_ashr_i32 s3, s3, 7
	s_ashr_i32 s2, s2, 7
	s_cmp_lt_i32 s74, s2
	s_cselect_b64 s[4:5], -1, 0
	s_and_b64 s[76:77], s[0:1], s[4:5]
	s_cmp_ge_i32 s74, s2
	s_cselect_b64 s[0:1], -1, 0
	s_add_i32 s3, s3, s2
	s_cmp_lt_i32 s74, s3
	s_cselect_b64 s[4:5], -1, 0
	s_and_b64 s[78:79], s[0:1], s[4:5]
	s_add_i32 s0, s56, 0x7f
	s_ashr_i32 s33, s0, 7
	s_cmp_ge_i32 s74, s3
	s_cselect_b64 s[0:1], -1, 0
	s_add_i32 s33, s33, s3
	s_cmp_lt_i32 s74, s33
	s_cselect_b64 s[4:5], -1, 0
	s_and_b64 s[82:83], s[0:1], s[4:5]
	s_add_i32 s0, s97, 0x7f
	s_ashr_i32 s58, s0, 7
	s_cmp_ge_i32 s74, s33
	s_cselect_b64 s[0:1], -1, 0
	s_add_i32 s58, s58, s33
	s_cmp_lt_i32 s74, s58
	s_cselect_b64 s[4:5], -1, 0
	s_and_b64 s[84:85], s[0:1], s[4:5]
	s_add_i32 s0, s96, 0x7f
	s_ashr_i32 s60, s0, 7
	s_cmp_ge_i32 s74, s58
	s_cselect_b64 s[0:1], -1, 0
	s_add_i32 s60, s60, s58
	s_cmp_lt_i32 s74, s60
	v_readfirstlane_b32 s63, v9
	s_cselect_b64 s[4:5], -1, 0
	s_and_b64 s[88:89], s[0:1], s[4:5]
	s_add_i32 s0, s63, 0x7f
	s_ashr_i32 s61, s0, 7
	s_cmp_ge_i32 s74, s60
	v_add_u32_e32 v9, 0x7f, v10
	s_cselect_b64 s[0:1], -1, 0
	s_add_i32 s61, s61, s60
	v_ashrrev_i32_e32 v9, 7, v9
	v_add_u32_e32 v42, s61, v9
	v_add_u32_e32 v9, 0x7f, v11
	v_ashrrev_i32_e32 v9, 7, v9
	v_add_u32_e32 v43, v9, v42
	v_add_u32_e32 v9, 0x7f, v4
	v_ashrrev_i32_e32 v9, 7, v9
	v_add_u32_e32 v44, v9, v43
	v_add_u32_e32 v9, 0x7f, v5
	v_ashrrev_i32_e32 v9, 7, v9
	v_add_u32_e32 v45, v9, v44
	v_add_u32_e32 v9, 0x7f, v6
	v_ashrrev_i32_e32 v9, 7, v9
	v_add_u32_e32 v46, v9, v45
	v_add_u32_e32 v9, 0x7f, v7
	v_ashrrev_i32_e32 v9, 7, v9
	v_add_u32_e32 v47, v9, v46
	v_add_u32_e32 v9, 0x7f, v0
	v_ashrrev_i32_e32 v9, 7, v9
	v_add_u32_e32 v48, v9, v47
	v_add_u32_e32 v9, 0x7f, v1
	v_ashrrev_i32_e32 v9, 7, v9
	v_add_u32_e32 v49, v9, v48
	v_add_u32_e32 v9, 0x7f, v2
	v_ashrrev_i32_e32 v9, 7, v9
	v_add_u32_e32 v50, v9, v49
	v_add_u32_e32 v9, 0x7f, v3
	v_ashrrev_i32_e32 v9, 7, v9
	v_add_u32_e32 v51, v9, v50
	s_cmp_lt_i32 s74, s61
	v_cndmask_b32_e64 v8, 0, 1, s[78:79]
	s_cselect_b64 s[4:5], -1, 0
	v_cndmask_b32_e64 v8, v8, 2, s[82:83]
	s_and_b64 s[90:91], s[0:1], s[4:5]
	v_cndmask_b32_e64 v8, v8, 3, s[84:85]
	s_waitcnt vmcnt(0)
	v_add_u32_e32 v9, 0x7f, v24
	v_ashrrev_i32_e32 v9, 7, v9
	v_add_u32_e32 v52, v9, v51
	v_add_u32_e32 v9, 0x7f, v25
	v_ashrrev_i32_e32 v9, 7, v9
	v_add_u32_e32 v53, v9, v52
	v_add_u32_e32 v9, 0x7f, v26
	v_ashrrev_i32_e32 v9, 7, v9
	v_add_u32_e32 v54, v9, v53
	v_add_u32_e32 v9, 0x7f, v27
	s_cmp_ge_i32 s74, s61
	v_ashrrev_i32_e32 v9, 7, v9
	v_cndmask_b32_e64 v8, v8, 4, s[88:89]
	s_cselect_b64 s[0:1], -1, 0
	v_cmp_lt_i32_e32 vcc, s74, v42
	v_add_u32_e32 v55, v9, v54
	v_add_u32_e32 v9, 0x7f, v20
	v_cndmask_b32_e64 v8, v8, 5, s[90:91]
	s_and_b64 vcc, s[0:1], vcc
	v_cmp_ge_i32_e64 s[0:1], s74, v42
	v_cmp_lt_i32_e64 s[4:5], s74, v43
	v_ashrrev_i32_e32 v9, 7, v9
	v_cndmask_b32_e64 v8, v8, 6, vcc
	s_and_b64 s[4:5], s[0:1], s[4:5]
	v_cmp_ge_i32_e64 s[0:1], s74, v43
	v_cmp_lt_i32_e64 s[6:7], s74, v44
	v_add_u32_e32 v56, v9, v55
	v_add_u32_e32 v9, 0x7f, v21
	v_cndmask_b32_e64 v8, v8, 7, s[4:5]
	s_and_b64 s[6:7], s[0:1], s[6:7]
	v_cmp_ge_i32_e64 s[0:1], s74, v44
	v_cmp_lt_i32_e64 s[8:9], s74, v45
	v_ashrrev_i32_e32 v9, 7, v9
	v_cndmask_b32_e64 v8, v8, 8, s[6:7]
	s_and_b64 s[8:9], s[0:1], s[8:9]
	v_cmp_ge_i32_e64 s[0:1], s74, v45
	v_cmp_lt_i32_e64 s[10:11], s74, v46
	v_add_u32_e32 v57, v9, v56
	v_add_u32_e32 v9, 0x7f, v22
	v_cndmask_b32_e64 v8, v8, 9, s[8:9]
	s_and_b64 s[10:11], s[0:1], s[10:11]
	v_cmp_ge_i32_e64 s[0:1], s74, v46
	v_cmp_lt_i32_e64 s[12:13], s74, v47
	v_ashrrev_i32_e32 v9, 7, v9
	v_cndmask_b32_e64 v8, v8, 10, s[10:11]
	s_and_b64 s[12:13], s[0:1], s[12:13]
	v_cmp_ge_i32_e64 s[0:1], s74, v47
	v_cmp_lt_i32_e64 s[14:15], s74, v48
	v_add_u32_e32 v58, v9, v57
	v_add_u32_e32 v9, 0x7f, v23
	v_cndmask_b32_e64 v8, v8, 11, s[12:13]
	s_and_b64 s[14:15], s[0:1], s[14:15]
	v_cmp_ge_i32_e64 s[0:1], s74, v48
	v_cmp_lt_i32_e64 s[16:17], s74, v49
	v_ashrrev_i32_e32 v9, 7, v9
	v_cndmask_b32_e64 v8, v8, 12, s[14:15]
	s_and_b64 s[16:17], s[0:1], s[16:17]
	v_cmp_ge_i32_e64 s[0:1], s74, v49
	v_cmp_lt_i32_e64 s[18:19], s74, v50
	v_add_u32_e32 v59, v9, v58
	v_add_u32_e32 v9, 0x7f, v16
	v_cndmask_b32_e64 v8, v8, 13, s[16:17]
	s_and_b64 s[18:19], s[0:1], s[18:19]
	v_cmp_ge_i32_e64 s[0:1], s74, v50
	v_cmp_lt_i32_e64 s[20:21], s74, v51
	v_ashrrev_i32_e32 v9, 7, v9
	v_cndmask_b32_e64 v8, v8, 14, s[18:19]
	s_and_b64 s[20:21], s[0:1], s[20:21]
	v_cmp_ge_i32_e64 s[0:1], s74, v51
	v_cmp_lt_i32_e64 s[22:23], s74, v52
	v_add_u32_e32 v60, v9, v59
	v_add_u32_e32 v9, 0x7f, v17
	v_cndmask_b32_e64 v8, v8, 15, s[20:21]
	s_and_b64 s[22:23], s[0:1], s[22:23]
	v_cmp_ge_i32_e64 s[0:1], s74, v52
	v_cmp_lt_i32_e64 s[24:25], s74, v53
	v_ashrrev_i32_e32 v9, 7, v9
	v_cndmask_b32_e64 v8, v8, 16, s[22:23]
	s_and_b64 s[24:25], s[0:1], s[24:25]
	v_cmp_ge_i32_e64 s[0:1], s74, v53
	v_cmp_lt_i32_e64 s[26:27], s74, v54
	v_add_u32_e32 v61, v9, v60
	v_add_u32_e32 v9, 0x7f, v18
	v_cndmask_b32_e64 v8, v8, 17, s[24:25]
	s_and_b64 s[26:27], s[0:1], s[26:27]
	v_cmp_ge_i32_e64 s[0:1], s74, v54
	v_cmp_lt_i32_e64 s[28:29], s74, v55
	v_ashrrev_i32_e32 v9, 7, v9
	v_cndmask_b32_e64 v8, v8, 18, s[26:27]
	s_and_b64 s[28:29], s[0:1], s[28:29]
	v_cmp_ge_i32_e64 s[0:1], s74, v55
	v_cmp_lt_i32_e64 s[30:31], s74, v56
	v_add_u32_e32 v62, v9, v61
	v_add_u32_e32 v9, 0x7f, v19
	v_cndmask_b32_e64 v8, v8, 19, s[28:29]
	s_and_b64 s[30:31], s[0:1], s[30:31]
	v_cmp_ge_i32_e64 s[0:1], s74, v56
	v_cmp_lt_i32_e64 s[34:35], s74, v57
	v_ashrrev_i32_e32 v9, 7, v9
	v_cndmask_b32_e64 v8, v8, 20, s[30:31]
	s_and_b64 s[34:35], s[0:1], s[34:35]
	v_cmp_ge_i32_e64 s[0:1], s74, v57
	v_cmp_lt_i32_e64 s[36:37], s74, v58
	v_add_u32_e32 v63, v9, v62
	v_add_u32_e32 v9, 0x7f, v12
	v_cndmask_b32_e64 v8, v8, 21, s[34:35]
	s_and_b64 s[36:37], s[0:1], s[36:37]
	v_cmp_ge_i32_e64 s[0:1], s74, v58
	v_cmp_lt_i32_e64 s[38:39], s74, v59
	v_ashrrev_i32_e32 v9, 7, v9
	v_cndmask_b32_e64 v8, v8, 22, s[36:37]
	s_and_b64 s[38:39], s[0:1], s[38:39]
	v_cmp_ge_i32_e64 s[0:1], s74, v59
	v_cmp_lt_i32_e64 s[40:41], s74, v60
	v_add_u32_e32 v64, v9, v63
	v_add_u32_e32 v9, 0x7f, v13
	v_cndmask_b32_e64 v8, v8, 23, s[38:39]
	s_and_b64 s[40:41], s[0:1], s[40:41]
	v_cmp_ge_i32_e64 s[0:1], s74, v60
	v_cmp_lt_i32_e64 s[42:43], s74, v61
	v_ashrrev_i32_e32 v9, 7, v9
	v_cndmask_b32_e64 v8, v8, 24, s[40:41]
	s_and_b64 s[42:43], s[0:1], s[42:43]
	v_cmp_ge_i32_e64 s[0:1], s74, v61
	v_cmp_lt_i32_e64 s[44:45], s74, v62
	v_add_u32_e32 v65, v9, v64
	v_add_u32_e32 v9, 0x7f, v14
	v_cndmask_b32_e64 v8, v8, 25, s[42:43]
	s_and_b64 s[44:45], s[0:1], s[44:45]
	v_cmp_ge_i32_e64 s[0:1], s74, v62
	v_cmp_lt_i32_e64 s[46:47], s74, v63
	v_ashrrev_i32_e32 v9, 7, v9
	v_cndmask_b32_e64 v8, v8, 26, s[44:45]
	s_and_b64 s[46:47], s[0:1], s[46:47]
	v_cmp_ge_i32_e64 s[0:1], s74, v63
	v_cmp_lt_i32_e64 s[48:49], s74, v64
	v_add_u32_e32 v95, v9, v65
	v_add_u32_e32 v9, 0x7f, v15
	v_cndmask_b32_e64 v8, v8, 27, s[46:47]
	s_and_b64 s[48:49], s[0:1], s[48:49]
	v_cmp_ge_i32_e64 s[0:1], s74, v64
	v_cmp_lt_i32_e64 s[50:51], s74, v65
	v_ashrrev_i32_e32 v9, 7, v9
	v_cndmask_b32_e64 v8, v8, 28, s[48:49]
	s_and_b64 s[50:51], s[0:1], s[50:51]
	v_cmp_ge_i32_e64 s[0:1], s74, v65
	v_cmp_lt_i32_e64 s[52:53], s74, v95
	v_add_u32_e32 v9, v9, v95
	v_cndmask_b32_e64 v8, v8, 29, s[50:51]
	s_and_b64 s[52:53], s[0:1], s[52:53]
	v_cmp_ge_i32_e64 s[0:1], s74, v95
	v_cmp_lt_i32_e64 s[54:55], s74, v9
	v_cndmask_b32_e64 v8, v8, 30, s[52:53]
	s_and_b64 s[54:55], s[0:1], s[54:55]
	v_cndmask_b32_e64 v92, v8, 31, s[54:55]
	s_and_b32 s70, s59, 0x780
	s_ashr_i32 s75, s74, 31
	v_lshl_add_u64 v[28:29], s[70:71], 0, v[128:129]
	v_lshlrev_b64 v[30:31], 21, v[92:93]
	s_lshl_b64 s[0:1], s[74:75], 17
	v_lshlrev_b64 v[28:29], 10, v[28:29]
	v_lshl_add_u64 v[30:31], v[96:97], 0, v[30:31]
	v_lshl_add_u64 v[8:9], v[100:101], 0, s[0:1]
	v_lshl_add_u64 v[28:29], v[30:31], 0, v[28:29]
	s_mov_b64 s[0:1], 0x8000
	v_lshl_add_u64 v[40:41], v[8:9], 0, s[0:1]
	v_lshl_add_u64 v[38:39], v[28:29], 0, s[0:1]
	s_mov_b64 s[0:1], 0x10000
	v_lshl_add_u64 v[36:37], v[8:9], 0, s[0:1]
	v_lshl_add_u64 v[34:35], v[28:29], 0, s[0:1]
	s_mov_b64 s[0:1], 0x18000
	s_sub_i32 s2, s74, s2
	s_sub_i32 s3, s74, s3
	s_sub_i32 s33, s74, s33
	s_sub_i32 s58, s74, s58
	s_sub_i32 s60, s74, s60
	s_sub_i32 s61, s74, s61
	v_lshl_add_u64 v[32:33], v[8:9], 0, s[0:1]
	v_lshl_add_u64 v[30:31], v[28:29], 0, s[0:1]
	s_and_b64 s[0:1], s[76:77], exec
	s_cselect_b32 s64, s74, 0
	s_and_b64 s[0:1], s[78:79], exec
	s_cselect_b32 s2, s2, s64
	s_and_b64 s[0:1], s[82:83], exec
	s_cselect_b32 s2, s3, s2
	s_and_b64 s[0:1], s[84:85], exec
	s_cselect_b32 s2, s33, s2
	s_and_b64 s[0:1], s[88:89], exec
	s_cselect_b32 s2, s58, s2
	s_and_b64 s[0:1], s[90:91], exec
	s_cselect_b32 s2, s60, s2
	s_and_b64 s[0:1], vcc, exec
	s_cselect_b32 s0, s61, s2
	v_sub_u32_e32 v42, s74, v42
	v_sub_u32_e32 v106, s74, v65
	v_mov_b32_e32 v65, s0
	v_sub_u32_e32 v43, s74, v43
	v_cndmask_b32_e64 v42, v65, v42, s[4:5]
	v_sub_u32_e32 v44, s74, v44
	v_cndmask_b32_e64 v42, v42, v43, s[6:7]
	v_sub_u32_e32 v45, s74, v45
	v_cndmask_b32_e64 v42, v42, v44, s[8:9]
	v_sub_u32_e32 v46, s74, v46
	v_cndmask_b32_e64 v42, v42, v45, s[10:11]
	v_sub_u32_e32 v47, s74, v47
	v_cndmask_b32_e64 v42, v42, v46, s[12:13]
	v_sub_u32_e32 v48, s74, v48
	v_cndmask_b32_e64 v42, v42, v47, s[14:15]
	v_sub_u32_e32 v49, s74, v49
	v_cndmask_b32_e64 v42, v42, v48, s[16:17]
	v_sub_u32_e32 v50, s74, v50
	v_cndmask_b32_e64 v42, v42, v49, s[18:19]
	v_sub_u32_e32 v51, s74, v51
	v_cndmask_b32_e64 v42, v42, v50, s[20:21]
	v_sub_u32_e32 v52, s74, v52
	v_cndmask_b32_e64 v42, v42, v51, s[22:23]
	v_sub_u32_e32 v53, s74, v53
	v_cndmask_b32_e64 v42, v42, v52, s[24:25]
	v_sub_u32_e32 v54, s74, v54
	v_cndmask_b32_e64 v42, v42, v53, s[26:27]
	v_sub_u32_e32 v55, s74, v55
	v_cndmask_b32_e64 v42, v42, v54, s[28:29]
	v_sub_u32_e32 v56, s74, v56
	v_cndmask_b32_e64 v42, v42, v55, s[30:31]
	v_sub_u32_e32 v57, s74, v57
	v_cndmask_b32_e64 v42, v42, v56, s[34:35]
	v_sub_u32_e32 v58, s74, v58
	v_cndmask_b32_e64 v42, v42, v57, s[36:37]
	v_sub_u32_e32 v59, s74, v59
	v_cndmask_b32_e64 v42, v42, v58, s[38:39]
	v_sub_u32_e32 v60, s74, v60
	v_cndmask_b32_e64 v42, v42, v59, s[40:41]
	v_sub_u32_e32 v61, s74, v61
	v_cndmask_b32_e64 v42, v42, v60, s[42:43]
	v_sub_u32_e32 v62, s74, v62
	v_cndmask_b32_e64 v42, v42, v61, s[44:45]
	v_sub_u32_e32 v63, s74, v63
	v_cndmask_b32_e64 v42, v42, v62, s[46:47]
	v_sub_u32_e32 v64, s74, v64
	v_cndmask_b32_e64 v42, v42, v63, s[48:49]
	v_cndmask_b32_e64 v107, v42, v64, s[50:51]
	v_mov_b32_e32 v42, v199
	s_nop 0
	v_lshlrev_b32_e32 v44, 4, v42
	v_add_u32_e32 v45, 0x8000, v44
	v_readfirstlane_b32 s2, v44
	s_mov_b32 m0, s2
	v_readfirstlane_b32 s3, v45
	v_add_u32_e32 v45, 0x1000, v44
	s_barrier
	global_load_lds_dwordx4 v[8:9], off
	s_mov_b32 m0, s3
	v_readfirstlane_b32 s72, v45
	global_load_lds_dwordx4 v[28:29], off
	s_mov_b32 m0, s72
	v_lshrrev_b32_e32 v43, 4, v42
	global_load_lds_dwordx4 v[40:41], off
	v_add_u32_e32 v40, 0x9000, v44
	s_mov_b32 s0, 0x1ffffc0
	v_readfirstlane_b32 s73, v40
	s_mov_b32 m0, s73
	s_mov_b64 s[60:61], 0x80
	global_load_lds_dwordx4 v[38:39], off
	v_add_u32_e32 v38, 0x2000, v44
	s_nop 0
	v_readfirstlane_b32 s33, v38
	s_mov_b32 m0, s33
	s_nop 0
	global_load_lds_dwordx4 v[36:37], off
	v_add_u32_e32 v36, 0xa000, v44
	s_nop 0
	v_readfirstlane_b32 s64, v36
	s_mov_b32 m0, s64
	s_nop 0
	global_load_lds_dwordx4 v[34:35], off
	v_add_u32_e32 v34, 0x3000, v44
	s_nop 0
	v_readfirstlane_b32 s65, v34
	s_mov_b32 m0, s65
	s_nop 0
	global_load_lds_dwordx4 v[32:33], off
	v_add_u32_e32 v32, 0xb000, v44
	v_lshrrev_b32_e32 v33, 1, v42
	v_readfirstlane_b32 s58, v32
	s_mov_b32 m0, s58
	v_bfe_u32 v32, v42, 1, 3
	global_load_lds_dwordx4 v[30:31], off
	v_and_b32_e32 v30, 15, v42
	v_bfe_u32 v31, v42, 4, 2
	v_and_or_b32 v30, v33, s0, v30
	v_bitop3_b32 v33, v43, v32, 3 bitop3:0x6c
	v_bitop3_b32 v108, v31, v32, 4 bitop3:0x36
	v_add_u32_e32 v32, 0x4000, v44
	v_lshlrev_b32_e32 v90, 7, v30
	v_lshlrev_b32_e32 v30, 7, v42
	v_readfirstlane_b32 s0, v32
	v_add_u32_e32 v32, 0xc000, v44
	v_and_b32_e32 v91, 0x2780, v30
	v_lshl_add_u64 v[30:31], v[8:9], 0, s[60:61]
	s_mov_b32 m0, s0
	v_readfirstlane_b32 s1, v32
	v_add_u32_e32 v32, 0x5000, v44
	s_waitcnt vmcnt(0)
	s_waitcnt vmcnt(0) lgkmcnt(0)
	s_barrier
	global_load_lds_dwordx4 v[30:31], off
	v_lshl_add_u64 v[30:31], v[28:29], 0, s[60:61]
	s_mov_b32 m0, s1
	s_mov_b64 s[60:61], 0x8080
	v_readfirstlane_b32 s75, v32
	v_add_u32_e32 v32, 0xd000, v44
	global_load_lds_dwordx4 v[30:31], off
	v_lshl_add_u64 v[30:31], v[8:9], 0, s[60:61]
	s_mov_b32 m0, s75
	v_readfirstlane_b32 s81, v32
	v_add_u32_e32 v32, 0x6000, v44
	global_load_lds_dwordx4 v[30:31], off
	v_lshl_add_u64 v[30:31], v[28:29], 0, s[60:61]
	s_mov_b32 m0, s81
	s_mov_b64 s[60:61], 0x10080
	v_readfirstlane_b32 s86, v32
	v_add_u32_e32 v32, 0xe000, v44
	global_load_lds_dwordx4 v[30:31], off
	v_lshl_add_u64 v[30:31], v[8:9], 0, s[60:61]
	s_mov_b32 m0, s86
	v_readfirstlane_b32 s87, v32
	v_add_u32_e32 v32, 0x7000, v44
	global_load_lds_dwordx4 v[30:31], off
	v_lshl_add_u64 v[30:31], v[28:29], 0, s[60:61]
	s_mov_b32 m0, s87
	v_readfirstlane_b32 s60, v32
	v_add_u32_e32 v32, 0xf000, v44
	global_load_lds_dwordx4 v[30:31], off
	v_lshl_add_u64 v[30:31], v[8:9], 0, s[66:67]
	s_mov_b32 m0, s60
	v_readfirstlane_b32 s61, v32
	global_load_lds_dwordx4 v[30:31], off
	v_lshl_add_u64 v[30:31], v[28:29], 0, s[66:67]
	s_mov_b32 m0, s61
	v_lshlrev_b32_e32 v46, 4, v33
	global_load_lds_dwordx4 v[30:31], off
	v_or_b32_e32 v110, v90, v46
	v_or_b32_e32 v111, v91, v46
	ds_read_b128 v[30:33], v110
	ds_read_b128 v[34:37], v110 offset:2048
	ds_read_b128 v[38:41], v110 offset:4096
	ds_read_b128 v[42:45], v110 offset:6144
	ds_read_b128 v[46:49], v111 offset:32768
	ds_read_b128 v[50:53], v111 offset:34816
	ds_read_b128 v[54:57], v111 offset:36864
	ds_read_b128 v[58:61], v111 offset:38912
	v_lshlrev_b32_e32 v108, 4, v108
	s_mov_b64 s[66:67], 0x100
	v_or_b32_e32 v109, v90, v108
	v_or_b32_e32 v108, v91, v108
	v_lshl_add_u64 v[90:91], v[8:9], 0, s[66:67]
	s_mov_b32 m0, s2
	s_waitcnt lgkmcnt(0)
	v_mfma_f32_16x16x32_bf16 v[62:65], v[46:49], v[30:33], 0
	v_mfma_f32_16x16x32_bf16 v[66:69], v[50:53], v[30:33], 0
	v_mfma_f32_16x16x32_bf16 v[70:73], v[54:57], v[30:33], 0
	v_mfma_f32_16x16x32_bf16 v[30:33], v[58:61], v[30:33], 0
	v_mfma_f32_16x16x32_bf16 v[74:77], v[46:49], v[34:37], 0
	v_mfma_f32_16x16x32_bf16 v[78:81], v[50:53], v[34:37], 0
	v_mfma_f32_16x16x32_bf16 v[82:85], v[54:57], v[34:37], 0
	v_mfma_f32_16x16x32_bf16 v[34:37], v[58:61], v[34:37], 0
	v_mfma_f32_16x16x32_bf16 v[86:89], v[46:49], v[38:41], 0
	v_mfma_f32_16x16x32_bf16 v[112:115], v[50:53], v[38:41], 0
	v_mfma_f32_16x16x32_bf16 v[116:119], v[54:57], v[38:41], 0
	v_mfma_f32_16x16x32_bf16 v[38:41], v[58:61], v[38:41], 0
	v_mfma_f32_16x16x32_bf16 v[46:49], v[46:49], v[42:45], 0
	v_mfma_f32_16x16x32_bf16 v[50:53], v[50:53], v[42:45], 0
	v_mfma_f32_16x16x32_bf16 v[54:57], v[54:57], v[42:45], 0
	v_mfma_f32_16x16x32_bf16 v[42:45], v[58:61], v[42:45], 0
	ds_read_b128 v[58:61], v109
	ds_read_b128 v[120:123], v109 offset:2048
	ds_read_b128 v[124:127], v109 offset:4096
	ds_read_b128 v[130:133], v109 offset:6144
	ds_read_b128 v[134:137], v108 offset:32768
	ds_read_b128 v[138:141], v108 offset:34816
	ds_read_b128 v[142:145], v108 offset:36864
	ds_read_b128 v[146:149], v108 offset:38912
	s_waitcnt vmcnt(0)
	s_waitcnt vmcnt(0) lgkmcnt(0)
	s_barrier
	global_load_lds_dwordx4 v[90:91], off
	v_lshl_add_u64 v[90:91], v[28:29], 0, s[66:67]
	s_mov_b32 m0, s3
	s_mov_b64 s[66:67], 0x8100
	global_load_lds_dwordx4 v[90:91], off
	v_lshl_add_u64 v[90:91], v[8:9], 0, s[66:67]
	s_mov_b32 m0, s72
	v_mfma_f32_16x16x32_bf16 v[62:65], v[134:137], v[58:61], v[62:65]
	global_load_lds_dwordx4 v[90:91], off
	v_lshl_add_u64 v[90:91], v[28:29], 0, s[66:67]
	s_mov_b32 m0, s73
	s_mov_b64 s[66:67], 0x10100
	global_load_lds_dwordx4 v[90:91], off
	v_lshl_add_u64 v[90:91], v[8:9], 0, s[66:67]
	s_mov_b32 m0, s33
	v_mfma_f32_16x16x32_bf16 v[66:69], v[138:141], v[58:61], v[66:69]
	global_load_lds_dwordx4 v[90:91], off
	v_lshl_add_u64 v[90:91], v[28:29], 0, s[66:67]
	s_mov_b32 m0, s64
	s_mov_b64 s[66:67], 0x18100
	global_load_lds_dwordx4 v[90:91], off
	v_lshl_add_u64 v[90:91], v[8:9], 0, s[66:67]
	s_mov_b32 m0, s65
	v_mfma_f32_16x16x32_bf16 v[70:73], v[142:145], v[58:61], v[70:73]
	global_load_lds_dwordx4 v[90:91], off
	v_lshl_add_u64 v[90:91], v[28:29], 0, s[66:67]
	s_mov_b32 m0, s58
	v_mfma_f32_16x16x32_bf16 v[30:33], v[146:149], v[58:61], v[30:33]
	global_load_lds_dwordx4 v[90:91], off
	s_mov_b64 s[66:67], 0x180
	v_mfma_f32_16x16x32_bf16 v[58:61], v[134:137], v[120:123], v[74:77]
	v_lshl_add_u64 v[90:91], v[8:9], 0, s[66:67]
	s_mov_b32 m0, s0
	v_mfma_f32_16x16x32_bf16 v[74:77], v[138:141], v[120:123], v[78:81]
	v_mfma_f32_16x16x32_bf16 v[78:81], v[142:145], v[120:123], v[82:85]
	v_mfma_f32_16x16x32_bf16 v[34:37], v[146:149], v[120:123], v[34:37]
	v_mfma_f32_16x16x32_bf16 v[82:85], v[134:137], v[124:127], v[86:89]
	v_mfma_f32_16x16x32_bf16 v[86:89], v[138:141], v[124:127], v[112:115]
	v_mfma_f32_16x16x32_bf16 v[112:115], v[142:145], v[124:127], v[116:119]
	v_mfma_f32_16x16x32_bf16 v[38:41], v[146:149], v[124:127], v[38:41]
	v_mfma_f32_16x16x32_bf16 v[46:49], v[134:137], v[130:133], v[46:49]
	v_mfma_f32_16x16x32_bf16 v[50:53], v[138:141], v[130:133], v[50:53]
	v_mfma_f32_16x16x32_bf16 v[54:57], v[142:145], v[130:133], v[54:57]
	v_mfma_f32_16x16x32_bf16 v[42:45], v[146:149], v[130:133], v[42:45]
	ds_read_b128 v[116:119], v110 offset:16384
	ds_read_b128 v[120:123], v110 offset:18432
	ds_read_b128 v[124:127], v110 offset:20480
	ds_read_b128 v[130:133], v110 offset:22528
	ds_read_b128 v[134:137], v111 offset:49152
	ds_read_b128 v[138:141], v111 offset:51200
	ds_read_b128 v[142:145], v111 offset:53248
	ds_read_b128 v[146:149], v111 offset:55296
	s_waitcnt lgkmcnt(0)
	v_mfma_f32_16x16x32_bf16 v[62:65], v[134:137], v[116:119], v[62:65]
	v_mfma_f32_16x16x32_bf16 v[66:69], v[138:141], v[116:119], v[66:69]
	v_mfma_f32_16x16x32_bf16 v[70:73], v[142:145], v[116:119], v[70:73]
	v_mfma_f32_16x16x32_bf16 v[30:33], v[146:149], v[116:119], v[30:33]
	v_mfma_f32_16x16x32_bf16 v[58:61], v[134:137], v[120:123], v[58:61]
	v_mfma_f32_16x16x32_bf16 v[74:77], v[138:141], v[120:123], v[74:77]
	v_mfma_f32_16x16x32_bf16 v[78:81], v[142:145], v[120:123], v[78:81]
	v_mfma_f32_16x16x32_bf16 v[34:37], v[146:149], v[120:123], v[34:37]
	v_mfma_f32_16x16x32_bf16 v[82:85], v[134:137], v[124:127], v[82:85]
	v_mfma_f32_16x16x32_bf16 v[86:89], v[138:141], v[124:127], v[86:89]
	v_mfma_f32_16x16x32_bf16 v[112:115], v[142:145], v[124:127], v[112:115]
	v_mfma_f32_16x16x32_bf16 v[38:41], v[146:149], v[124:127], v[38:41]
	v_mfma_f32_16x16x32_bf16 v[46:49], v[134:137], v[130:133], v[46:49]
	v_mfma_f32_16x16x32_bf16 v[50:53], v[138:141], v[130:133], v[50:53]
	v_mfma_f32_16x16x32_bf16 v[54:57], v[142:145], v[130:133], v[54:57]
	v_mfma_f32_16x16x32_bf16 v[42:45], v[146:149], v[130:133], v[42:45]
	ds_read_b128 v[116:119], v109 offset:16384
	ds_read_b128 v[120:123], v109 offset:18432
	ds_read_b128 v[124:127], v109 offset:20480
	ds_read_b128 v[130:133], v109 offset:22528
	ds_read_b128 v[134:137], v108 offset:49152
	ds_read_b128 v[138:141], v108 offset:51200
	ds_read_b128 v[142:145], v108 offset:53248
	ds_read_b128 v[146:149], v108 offset:55296
	s_waitcnt vmcnt(0)
	s_waitcnt vmcnt(0) lgkmcnt(0)
	s_barrier
	global_load_lds_dwordx4 v[90:91], off
	v_lshl_add_u64 v[90:91], v[28:29], 0, s[66:67]
	s_mov_b32 m0, s1
	s_mov_b64 s[66:67], 0x8180
	global_load_lds_dwordx4 v[90:91], off
	v_lshl_add_u64 v[90:91], v[8:9], 0, s[66:67]
	s_mov_b32 m0, s75
	v_mfma_f32_16x16x32_bf16 v[62:65], v[134:137], v[116:119], v[62:65]
	global_load_lds_dwordx4 v[90:91], off
	v_lshl_add_u64 v[90:91], v[28:29], 0, s[66:67]
	s_mov_b32 m0, s81
	s_mov_b64 s[66:67], 0x10180
	global_load_lds_dwordx4 v[90:91], off
	v_lshl_add_u64 v[90:91], v[8:9], 0, s[66:67]
	s_mov_b32 m0, s86
	v_mfma_f32_16x16x32_bf16 v[66:69], v[138:141], v[116:119], v[66:69]
	global_load_lds_dwordx4 v[90:91], off
	v_lshl_add_u64 v[90:91], v[28:29], 0, s[66:67]
	s_mov_b32 m0, s87
	s_mov_b64 s[66:67], 0x18180
	global_load_lds_dwordx4 v[90:91], off
	v_lshl_add_u64 v[90:91], v[8:9], 0, s[66:67]
	s_mov_b32 m0, s60
	v_mfma_f32_16x16x32_bf16 v[70:73], v[142:145], v[116:119], v[70:73]
	global_load_lds_dwordx4 v[90:91], off
	v_lshl_add_u64 v[90:91], v[28:29], 0, s[66:67]
	s_mov_b32 m0, s61
	v_mfma_f32_16x16x32_bf16 v[30:33], v[146:149], v[116:119], v[30:33]
	global_load_lds_dwordx4 v[90:91], off
	s_mov_b64 s[66:67], 0x200
	v_mfma_f32_16x16x32_bf16 v[58:61], v[134:137], v[120:123], v[58:61]
	v_lshl_add_u64 v[90:91], v[8:9], 0, s[66:67]
	s_mov_b32 m0, s2
	v_mfma_f32_16x16x32_bf16 v[74:77], v[138:141], v[120:123], v[74:77]
	v_mfma_f32_16x16x32_bf16 v[78:81], v[142:145], v[120:123], v[78:81]
	v_mfma_f32_16x16x32_bf16 v[34:37], v[146:149], v[120:123], v[34:37]
	v_mfma_f32_16x16x32_bf16 v[82:85], v[134:137], v[124:127], v[82:85]
	v_mfma_f32_16x16x32_bf16 v[86:89], v[138:141], v[124:127], v[86:89]
	v_mfma_f32_16x16x32_bf16 v[112:115], v[142:145], v[124:127], v[112:115]
	v_mfma_f32_16x16x32_bf16 v[38:41], v[146:149], v[124:127], v[38:41]
	v_mfma_f32_16x16x32_bf16 v[46:49], v[134:137], v[130:133], v[46:49]
	v_mfma_f32_16x16x32_bf16 v[50:53], v[138:141], v[130:133], v[50:53]
	v_mfma_f32_16x16x32_bf16 v[54:57], v[142:145], v[130:133], v[54:57]
	v_mfma_f32_16x16x32_bf16 v[42:45], v[146:149], v[130:133], v[42:45]
	ds_read_b128 v[116:119], v110
	ds_read_b128 v[120:123], v110 offset:2048
	ds_read_b128 v[124:127], v110 offset:4096
	ds_read_b128 v[130:133], v110 offset:6144
	ds_read_b128 v[134:137], v111 offset:32768
	ds_read_b128 v[138:141], v111 offset:34816
	ds_read_b128 v[142:145], v111 offset:36864
	ds_read_b128 v[146:149], v111 offset:38912
	s_waitcnt lgkmcnt(0)
	v_mfma_f32_16x16x32_bf16 v[62:65], v[134:137], v[116:119], v[62:65]
	v_mfma_f32_16x16x32_bf16 v[66:69], v[138:141], v[116:119], v[66:69]
	v_mfma_f32_16x16x32_bf16 v[70:73], v[142:145], v[116:119], v[70:73]
	v_mfma_f32_16x16x32_bf16 v[30:33], v[146:149], v[116:119], v[30:33]
	v_mfma_f32_16x16x32_bf16 v[58:61], v[134:137], v[120:123], v[58:61]
	v_mfma_f32_16x16x32_bf16 v[74:77], v[138:141], v[120:123], v[74:77]
	v_mfma_f32_16x16x32_bf16 v[78:81], v[142:145], v[120:123], v[78:81]
	v_mfma_f32_16x16x32_bf16 v[34:37], v[146:149], v[120:123], v[34:37]
	v_mfma_f32_16x16x32_bf16 v[82:85], v[134:137], v[124:127], v[82:85]
	v_mfma_f32_16x16x32_bf16 v[86:89], v[138:141], v[124:127], v[86:89]
	v_mfma_f32_16x16x32_bf16 v[112:115], v[142:145], v[124:127], v[112:115]
	v_mfma_f32_16x16x32_bf16 v[38:41], v[146:149], v[124:127], v[38:41]
	v_mfma_f32_16x16x32_bf16 v[46:49], v[134:137], v[130:133], v[46:49]
	v_mfma_f32_16x16x32_bf16 v[50:53], v[138:141], v[130:133], v[50:53]
	v_mfma_f32_16x16x32_bf16 v[54:57], v[142:145], v[130:133], v[54:57]
	v_mfma_f32_16x16x32_bf16 v[42:45], v[146:149], v[130:133], v[42:45]
	ds_read_b128 v[116:119], v109
	ds_read_b128 v[120:123], v109 offset:2048
	ds_read_b128 v[124:127], v109 offset:4096
	ds_read_b128 v[130:133], v109 offset:6144
	ds_read_b128 v[134:137], v108 offset:32768
	ds_read_b128 v[138:141], v108 offset:34816
	ds_read_b128 v[142:145], v108 offset:36864
	ds_read_b128 v[146:149], v108 offset:38912
	s_waitcnt vmcnt(0)
	s_waitcnt vmcnt(0) lgkmcnt(0)
	s_barrier
	global_load_lds_dwordx4 v[90:91], off
	v_lshl_add_u64 v[90:91], v[28:29], 0, s[66:67]
	s_mov_b32 m0, s3
	s_mov_b64 s[66:67], 0x8200
	global_load_lds_dwordx4 v[90:91], off
	v_lshl_add_u64 v[90:91], v[8:9], 0, s[66:67]
	s_mov_b32 m0, s72
	v_mfma_f32_16x16x32_bf16 v[62:65], v[134:137], v[116:119], v[62:65]
	global_load_lds_dwordx4 v[90:91], off
	v_lshl_add_u64 v[90:91], v[28:29], 0, s[66:67]
	s_mov_b32 m0, s73
	s_mov_b64 s[66:67], 0x10200
	global_load_lds_dwordx4 v[90:91], off
	v_lshl_add_u64 v[90:91], v[8:9], 0, s[66:67]
	s_mov_b32 m0, s33
	v_mfma_f32_16x16x32_bf16 v[66:69], v[138:141], v[116:119], v[66:69]
	global_load_lds_dwordx4 v[90:91], off
	v_lshl_add_u64 v[90:91], v[28:29], 0, s[66:67]
	s_mov_b32 m0, s64
	s_mov_b64 s[66:67], 0x18200
	global_load_lds_dwordx4 v[90:91], off
	v_lshl_add_u64 v[90:91], v[8:9], 0, s[66:67]
	s_mov_b32 m0, s65
	v_mfma_f32_16x16x32_bf16 v[70:73], v[142:145], v[116:119], v[70:73]
	global_load_lds_dwordx4 v[90:91], off
	v_lshl_add_u64 v[90:91], v[28:29], 0, s[66:67]
	s_mov_b32 m0, s58
	v_mfma_f32_16x16x32_bf16 v[30:33], v[146:149], v[116:119], v[30:33]
	global_load_lds_dwordx4 v[90:91], off
	s_mov_b64 s[66:67], 0x280
	v_mfma_f32_16x16x32_bf16 v[58:61], v[134:137], v[120:123], v[58:61]
	v_lshl_add_u64 v[90:91], v[8:9], 0, s[66:67]
	s_mov_b32 m0, s0
	v_mfma_f32_16x16x32_bf16 v[74:77], v[138:141], v[120:123], v[74:77]
	v_mfma_f32_16x16x32_bf16 v[78:81], v[142:145], v[120:123], v[78:81]
	v_mfma_f32_16x16x32_bf16 v[34:37], v[146:149], v[120:123], v[34:37]
	v_mfma_f32_16x16x32_bf16 v[82:85], v[134:137], v[124:127], v[82:85]
	v_mfma_f32_16x16x32_bf16 v[86:89], v[138:141], v[124:127], v[86:89]
	v_mfma_f32_16x16x32_bf16 v[112:115], v[142:145], v[124:127], v[112:115]
	v_mfma_f32_16x16x32_bf16 v[38:41], v[146:149], v[124:127], v[38:41]
	v_mfma_f32_16x16x32_bf16 v[46:49], v[134:137], v[130:133], v[46:49]
	v_mfma_f32_16x16x32_bf16 v[50:53], v[138:141], v[130:133], v[50:53]
	v_mfma_f32_16x16x32_bf16 v[54:57], v[142:145], v[130:133], v[54:57]
	v_mfma_f32_16x16x32_bf16 v[42:45], v[146:149], v[130:133], v[42:45]
	ds_read_b128 v[116:119], v110 offset:16384
	ds_read_b128 v[120:123], v110 offset:18432
	ds_read_b128 v[124:127], v110 offset:20480
	ds_read_b128 v[130:133], v110 offset:22528
	ds_read_b128 v[134:137], v111 offset:49152
	ds_read_b128 v[138:141], v111 offset:51200
	ds_read_b128 v[142:145], v111 offset:53248
	ds_read_b128 v[146:149], v111 offset:55296
	s_waitcnt lgkmcnt(0)
	v_mfma_f32_16x16x32_bf16 v[62:65], v[134:137], v[116:119], v[62:65]
	v_mfma_f32_16x16x32_bf16 v[66:69], v[138:141], v[116:119], v[66:69]
	v_mfma_f32_16x16x32_bf16 v[70:73], v[142:145], v[116:119], v[70:73]
	v_mfma_f32_16x16x32_bf16 v[30:33], v[146:149], v[116:119], v[30:33]
	v_mfma_f32_16x16x32_bf16 v[58:61], v[134:137], v[120:123], v[58:61]
	v_mfma_f32_16x16x32_bf16 v[74:77], v[138:141], v[120:123], v[74:77]
	v_mfma_f32_16x16x32_bf16 v[78:81], v[142:145], v[120:123], v[78:81]
	v_mfma_f32_16x16x32_bf16 v[34:37], v[146:149], v[120:123], v[34:37]
	v_mfma_f32_16x16x32_bf16 v[82:85], v[134:137], v[124:127], v[82:85]
	v_mfma_f32_16x16x32_bf16 v[86:89], v[138:141], v[124:127], v[86:89]
	v_mfma_f32_16x16x32_bf16 v[112:115], v[142:145], v[124:127], v[112:115]
	v_mfma_f32_16x16x32_bf16 v[38:41], v[146:149], v[124:127], v[38:41]
	v_mfma_f32_16x16x32_bf16 v[46:49], v[134:137], v[130:133], v[46:49]
	v_mfma_f32_16x16x32_bf16 v[50:53], v[138:141], v[130:133], v[50:53]
	v_mfma_f32_16x16x32_bf16 v[54:57], v[142:145], v[130:133], v[54:57]
	v_mfma_f32_16x16x32_bf16 v[42:45], v[146:149], v[130:133], v[42:45]
	ds_read_b128 v[116:119], v109 offset:16384
	ds_read_b128 v[120:123], v109 offset:18432
	ds_read_b128 v[124:127], v109 offset:20480
	ds_read_b128 v[130:133], v109 offset:22528
	ds_read_b128 v[134:137], v108 offset:49152
	ds_read_b128 v[138:141], v108 offset:51200
	ds_read_b128 v[142:145], v108 offset:53248
	ds_read_b128 v[146:149], v108 offset:55296
	s_waitcnt vmcnt(0)
	s_waitcnt vmcnt(0) lgkmcnt(0)
	s_barrier
	global_load_lds_dwordx4 v[90:91], off
	v_lshl_add_u64 v[90:91], v[28:29], 0, s[66:67]
	s_mov_b32 m0, s1
	s_mov_b64 s[66:67], 0x8280
	global_load_lds_dwordx4 v[90:91], off
	v_lshl_add_u64 v[90:91], v[8:9], 0, s[66:67]
	s_mov_b32 m0, s75
	v_mfma_f32_16x16x32_bf16 v[62:65], v[134:137], v[116:119], v[62:65]
	global_load_lds_dwordx4 v[90:91], off
	v_lshl_add_u64 v[90:91], v[28:29], 0, s[66:67]
	s_mov_b32 m0, s81
	s_mov_b64 s[66:67], 0x10280
	global_load_lds_dwordx4 v[90:91], off
	v_lshl_add_u64 v[90:91], v[8:9], 0, s[66:67]
	s_mov_b32 m0, s86
	v_mfma_f32_16x16x32_bf16 v[66:69], v[138:141], v[116:119], v[66:69]
	global_load_lds_dwordx4 v[90:91], off
	v_lshl_add_u64 v[90:91], v[28:29], 0, s[66:67]
	s_mov_b32 m0, s87
	s_mov_b64 s[66:67], 0x18280
	global_load_lds_dwordx4 v[90:91], off
	v_lshl_add_u64 v[90:91], v[8:9], 0, s[66:67]
	s_mov_b32 m0, s60
	v_mfma_f32_16x16x32_bf16 v[70:73], v[142:145], v[116:119], v[70:73]
	global_load_lds_dwordx4 v[90:91], off
	v_lshl_add_u64 v[90:91], v[28:29], 0, s[66:67]
	s_mov_b32 m0, s61
	v_mfma_f32_16x16x32_bf16 v[30:33], v[146:149], v[116:119], v[30:33]
	global_load_lds_dwordx4 v[90:91], off
	s_mov_b64 s[66:67], 0x300
	v_mfma_f32_16x16x32_bf16 v[58:61], v[134:137], v[120:123], v[58:61]
	v_lshl_add_u64 v[90:91], v[8:9], 0, s[66:67]
	s_mov_b32 m0, s2
	v_mfma_f32_16x16x32_bf16 v[74:77], v[138:141], v[120:123], v[74:77]
	v_mfma_f32_16x16x32_bf16 v[78:81], v[142:145], v[120:123], v[78:81]
	v_mfma_f32_16x16x32_bf16 v[34:37], v[146:149], v[120:123], v[34:37]
	v_mfma_f32_16x16x32_bf16 v[82:85], v[134:137], v[124:127], v[82:85]
	v_mfma_f32_16x16x32_bf16 v[86:89], v[138:141], v[124:127], v[86:89]
	v_mfma_f32_16x16x32_bf16 v[112:115], v[142:145], v[124:127], v[112:115]
	v_mfma_f32_16x16x32_bf16 v[38:41], v[146:149], v[124:127], v[38:41]
	v_mfma_f32_16x16x32_bf16 v[46:49], v[134:137], v[130:133], v[46:49]
	v_mfma_f32_16x16x32_bf16 v[50:53], v[138:141], v[130:133], v[50:53]
	v_mfma_f32_16x16x32_bf16 v[54:57], v[142:145], v[130:133], v[54:57]
	v_mfma_f32_16x16x32_bf16 v[42:45], v[146:149], v[130:133], v[42:45]
	ds_read_b128 v[116:119], v110
	ds_read_b128 v[120:123], v110 offset:2048
	ds_read_b128 v[124:127], v110 offset:4096
	ds_read_b128 v[130:133], v110 offset:6144
	ds_read_b128 v[134:137], v111 offset:32768
	ds_read_b128 v[138:141], v111 offset:34816
	ds_read_b128 v[142:145], v111 offset:36864
	ds_read_b128 v[146:149], v111 offset:38912
	s_waitcnt lgkmcnt(0)
	v_mfma_f32_16x16x32_bf16 v[62:65], v[134:137], v[116:119], v[62:65]
	v_mfma_f32_16x16x32_bf16 v[66:69], v[138:141], v[116:119], v[66:69]
	v_mfma_f32_16x16x32_bf16 v[70:73], v[142:145], v[116:119], v[70:73]
	v_mfma_f32_16x16x32_bf16 v[30:33], v[146:149], v[116:119], v[30:33]
	v_mfma_f32_16x16x32_bf16 v[58:61], v[134:137], v[120:123], v[58:61]
	v_mfma_f32_16x16x32_bf16 v[74:77], v[138:141], v[120:123], v[74:77]
	v_mfma_f32_16x16x32_bf16 v[78:81], v[142:145], v[120:123], v[78:81]
	v_mfma_f32_16x16x32_bf16 v[34:37], v[146:149], v[120:123], v[34:37]
	v_mfma_f32_16x16x32_bf16 v[82:85], v[134:137], v[124:127], v[82:85]
	v_mfma_f32_16x16x32_bf16 v[86:89], v[138:141], v[124:127], v[86:89]
	v_mfma_f32_16x16x32_bf16 v[112:115], v[142:145], v[124:127], v[112:115]
	v_mfma_f32_16x16x32_bf16 v[38:41], v[146:149], v[124:127], v[38:41]
	v_mfma_f32_16x16x32_bf16 v[46:49], v[134:137], v[130:133], v[46:49]
	v_mfma_f32_16x16x32_bf16 v[50:53], v[138:141], v[130:133], v[50:53]
	v_mfma_f32_16x16x32_bf16 v[54:57], v[142:145], v[130:133], v[54:57]
	v_mfma_f32_16x16x32_bf16 v[42:45], v[146:149], v[130:133], v[42:45]
	ds_read_b128 v[116:119], v109
	ds_read_b128 v[120:123], v109 offset:2048
	ds_read_b128 v[124:127], v109 offset:4096
	ds_read_b128 v[130:133], v109 offset:6144
	ds_read_b128 v[134:137], v108 offset:32768
	ds_read_b128 v[138:141], v108 offset:34816
	ds_read_b128 v[142:145], v108 offset:36864
	ds_read_b128 v[146:149], v108 offset:38912
	s_waitcnt vmcnt(0)
	s_waitcnt vmcnt(0) lgkmcnt(0)
	s_barrier
	global_load_lds_dwordx4 v[90:91], off
	v_lshl_add_u64 v[90:91], v[28:29], 0, s[66:67]
	s_mov_b32 m0, s3
	s_mov_b64 s[2:3], 0x8300
	global_load_lds_dwordx4 v[90:91], off
	v_lshl_add_u64 v[90:91], v[8:9], 0, s[2:3]
	s_mov_b32 m0, s72
	v_mfma_f32_16x16x32_bf16 v[62:65], v[134:137], v[116:119], v[62:65]
	global_load_lds_dwordx4 v[90:91], off
	v_lshl_add_u64 v[90:91], v[28:29], 0, s[2:3]
	s_mov_b32 m0, s73
	s_mov_b64 s[2:3], 0x10300
	global_load_lds_dwordx4 v[90:91], off
	v_lshl_add_u64 v[90:91], v[8:9], 0, s[2:3]
	s_mov_b32 m0, s33
	v_mfma_f32_16x16x32_bf16 v[66:69], v[138:141], v[116:119], v[66:69]
	global_load_lds_dwordx4 v[90:91], off
	v_lshl_add_u64 v[90:91], v[28:29], 0, s[2:3]
	s_mov_b32 m0, s64
	s_mov_b64 s[2:3], 0x18300
	global_load_lds_dwordx4 v[90:91], off
	v_lshl_add_u64 v[90:91], v[8:9], 0, s[2:3]
	s_mov_b32 m0, s65
	v_mfma_f32_16x16x32_bf16 v[70:73], v[142:145], v[116:119], v[70:73]
	global_load_lds_dwordx4 v[90:91], off
	v_lshl_add_u64 v[90:91], v[28:29], 0, s[2:3]
	s_mov_b32 m0, s58
	v_mfma_f32_16x16x32_bf16 v[30:33], v[146:149], v[116:119], v[30:33]
	global_load_lds_dwordx4 v[90:91], off
	s_mov_b64 s[2:3], 0x380
	v_mfma_f32_16x16x32_bf16 v[58:61], v[134:137], v[120:123], v[58:61]
	v_lshl_add_u64 v[90:91], v[8:9], 0, s[2:3]
	s_mov_b32 m0, s0
	v_mfma_f32_16x16x32_bf16 v[74:77], v[138:141], v[120:123], v[74:77]
	v_mfma_f32_16x16x32_bf16 v[78:81], v[142:145], v[120:123], v[78:81]
	v_mfma_f32_16x16x32_bf16 v[34:37], v[146:149], v[120:123], v[34:37]
	v_mfma_f32_16x16x32_bf16 v[82:85], v[134:137], v[124:127], v[82:85]
	v_mfma_f32_16x16x32_bf16 v[86:89], v[138:141], v[124:127], v[86:89]
	v_mfma_f32_16x16x32_bf16 v[112:115], v[142:145], v[124:127], v[112:115]
	v_mfma_f32_16x16x32_bf16 v[38:41], v[146:149], v[124:127], v[38:41]
	v_mfma_f32_16x16x32_bf16 v[46:49], v[134:137], v[130:133], v[46:49]
	v_mfma_f32_16x16x32_bf16 v[50:53], v[138:141], v[130:133], v[50:53]
	v_mfma_f32_16x16x32_bf16 v[54:57], v[142:145], v[130:133], v[54:57]
	v_mfma_f32_16x16x32_bf16 v[42:45], v[146:149], v[130:133], v[42:45]
	ds_read_b128 v[116:119], v110 offset:16384
	ds_read_b128 v[120:123], v110 offset:18432
	ds_read_b128 v[124:127], v110 offset:20480
	ds_read_b128 v[130:133], v110 offset:22528
	ds_read_b128 v[134:137], v111 offset:49152
	ds_read_b128 v[138:141], v111 offset:51200
	ds_read_b128 v[142:145], v111 offset:53248
	ds_read_b128 v[146:149], v111 offset:55296
	s_waitcnt lgkmcnt(0)
	v_mfma_f32_16x16x32_bf16 v[62:65], v[134:137], v[116:119], v[62:65]
	v_mfma_f32_16x16x32_bf16 v[66:69], v[138:141], v[116:119], v[66:69]
	v_mfma_f32_16x16x32_bf16 v[70:73], v[142:145], v[116:119], v[70:73]
	v_mfma_f32_16x16x32_bf16 v[30:33], v[146:149], v[116:119], v[30:33]
	v_mfma_f32_16x16x32_bf16 v[58:61], v[134:137], v[120:123], v[58:61]
	v_mfma_f32_16x16x32_bf16 v[74:77], v[138:141], v[120:123], v[74:77]
	v_mfma_f32_16x16x32_bf16 v[78:81], v[142:145], v[120:123], v[78:81]
	v_mfma_f32_16x16x32_bf16 v[34:37], v[146:149], v[120:123], v[34:37]
	v_mfma_f32_16x16x32_bf16 v[82:85], v[134:137], v[124:127], v[82:85]
	v_mfma_f32_16x16x32_bf16 v[86:89], v[138:141], v[124:127], v[86:89]
	v_mfma_f32_16x16x32_bf16 v[112:115], v[142:145], v[124:127], v[112:115]
	v_mfma_f32_16x16x32_bf16 v[38:41], v[146:149], v[124:127], v[38:41]
	v_mfma_f32_16x16x32_bf16 v[46:49], v[134:137], v[130:133], v[46:49]
	v_mfma_f32_16x16x32_bf16 v[50:53], v[138:141], v[130:133], v[50:53]
	v_mfma_f32_16x16x32_bf16 v[54:57], v[142:145], v[130:133], v[54:57]
	v_mfma_f32_16x16x32_bf16 v[42:45], v[146:149], v[130:133], v[42:45]
	ds_read_b128 v[116:119], v109 offset:16384
	ds_read_b128 v[120:123], v109 offset:18432
	ds_read_b128 v[124:127], v109 offset:20480
	ds_read_b128 v[130:133], v109 offset:22528
	ds_read_b128 v[134:137], v108 offset:49152
	ds_read_b128 v[138:141], v108 offset:51200
	ds_read_b128 v[142:145], v108 offset:53248
	ds_read_b128 v[146:149], v108 offset:55296
	s_waitcnt vmcnt(0)
	s_waitcnt vmcnt(0) lgkmcnt(0)
	s_barrier
	global_load_lds_dwordx4 v[90:91], off
	v_lshl_add_u64 v[90:91], v[28:29], 0, s[2:3]
	s_mov_b32 m0, s1
	s_mov_b64 s[0:1], 0x8380
	global_load_lds_dwordx4 v[90:91], off
	v_lshl_add_u64 v[90:91], v[8:9], 0, s[0:1]
	s_mov_b32 m0, s75
	v_mfma_f32_16x16x32_bf16 v[62:65], v[134:137], v[116:119], v[62:65]
	global_load_lds_dwordx4 v[90:91], off
	v_lshl_add_u64 v[90:91], v[28:29], 0, s[0:1]
	s_mov_b32 m0, s81
	s_mov_b64 s[0:1], 0x10380
	global_load_lds_dwordx4 v[90:91], off
	v_lshl_add_u64 v[90:91], v[8:9], 0, s[0:1]
	s_mov_b32 m0, s86
	v_mfma_f32_16x16x32_bf16 v[66:69], v[138:141], v[116:119], v[66:69]
	global_load_lds_dwordx4 v[90:91], off
	v_lshl_add_u64 v[90:91], v[28:29], 0, s[0:1]
	s_mov_b32 m0, s87
	s_mov_b64 s[0:1], 0x18380
	global_load_lds_dwordx4 v[90:91], off
	v_lshl_add_u64 v[8:9], v[8:9], 0, s[0:1]
	s_mov_b32 m0, s60
	v_mfma_f32_16x16x32_bf16 v[70:73], v[142:145], v[116:119], v[70:73]
	global_load_lds_dwordx4 v[8:9], off
	v_lshl_add_u64 v[8:9], v[28:29], 0, s[0:1]
	s_mov_b32 m0, s61
	s_and_b64 s[0:1], s[76:77], exec
	global_load_lds_dwordx4 v[8:9], off
	s_cselect_b32 s2, s80, 0
	s_and_b64 s[0:1], s[78:79], exec
	s_cselect_b32 s2, s57, s2
	s_and_b64 s[0:1], s[82:83], exec
	s_cselect_b32 s2, s56, s2
	s_and_b64 s[0:1], s[84:85], exec
	s_cselect_b32 s2, s97, s2
	s_and_b64 s[0:1], s[88:89], exec
	s_cselect_b32 s2, s96, s2
	s_and_b64 s[0:1], s[90:91], exec
	s_cselect_b32 s0, s63, s2
	v_mov_b32_e32 v8, s0
	v_cndmask_b32_e32 v8, v8, v10, vcc
	v_cndmask_b32_e64 v8, v8, v11, s[4:5]
	v_cndmask_b32_e64 v4, v8, v4, s[6:7]
	v_cndmask_b32_e64 v4, v4, v5, s[8:9]
	v_cndmask_b32_e64 v4, v4, v6, s[10:11]
	v_cndmask_b32_e64 v4, v4, v7, s[12:13]
	v_cndmask_b32_e64 v0, v4, v0, s[14:15]
	v_cndmask_b32_e64 v0, v0, v1, s[16:17]
	v_cndmask_b32_e64 v0, v0, v2, s[18:19]
	v_cndmask_b32_e64 v0, v0, v3, s[20:21]
	v_cndmask_b32_e64 v0, v0, v24, s[22:23]
	v_cndmask_b32_e64 v0, v0, v25, s[24:25]
	v_cndmask_b32_e64 v0, v0, v26, s[26:27]
	v_cndmask_b32_e64 v0, v0, v27, s[28:29]
	v_cndmask_b32_e64 v0, v0, v20, s[30:31]
	v_cndmask_b32_e64 v0, v0, v21, s[34:35]
	v_mfma_f32_16x16x32_bf16 v[30:33], v[146:149], v[116:119], v[30:33]
	v_cndmask_b32_e64 v0, v0, v22, s[36:37]
	v_cndmask_b32_e64 v0, v0, v23, s[38:39]
	v_cndmask_b32_e64 v0, v0, v16, s[40:41]
	v_mfma_f32_16x16x32_bf16 v[58:61], v[134:137], v[120:123], v[58:61]
	v_cndmask_b32_e64 v0, v0, v17, s[42:43]
	v_cndmask_b32_e64 v0, v0, v18, s[44:45]
	v_cndmask_b32_e64 v0, v0, v19, s[46:47]
	v_mfma_f32_16x16x32_bf16 v[74:77], v[138:141], v[120:123], v[74:77]
	v_cndmask_b32_e64 v0, v0, v12, s[48:49]
	v_cndmask_b32_e64 v0, v0, v13, s[50:51]
	v_cndmask_b32_e64 v0, v0, v14, s[52:53]
	v_mfma_f32_16x16x32_bf16 v[78:81], v[142:145], v[120:123], v[78:81]
	v_cndmask_b32_e64 v1, v107, v106, s[52:53]
	s_lshl_b32 s70, s70, 1
	v_mfma_f32_16x16x32_bf16 v[34:37], v[146:149], v[120:123], v[34:37]
	v_mfma_f32_16x16x32_bf16 v[82:85], v[134:137], v[124:127], v[82:85]
	v_mfma_f32_16x16x32_bf16 v[86:89], v[138:141], v[124:127], v[86:89]
	v_mfma_f32_16x16x32_bf16 v[112:115], v[142:145], v[124:127], v[112:115]
	v_mfma_f32_16x16x32_bf16 v[38:41], v[146:149], v[124:127], v[38:41]
	v_mfma_f32_16x16x32_bf16 v[46:49], v[134:137], v[130:133], v[46:49]
	v_mfma_f32_16x16x32_bf16 v[50:53], v[138:141], v[130:133], v[50:53]
	v_mfma_f32_16x16x32_bf16 v[54:57], v[142:145], v[130:133], v[54:57]
	v_mfma_f32_16x16x32_bf16 v[42:45], v[146:149], v[130:133], v[42:45]
	ds_read_b128 v[116:119], v110
	ds_read_b128 v[120:123], v110 offset:2048
	ds_read_b128 v[124:127], v110 offset:4096
	ds_read_b128 v[130:133], v110 offset:6144
	ds_read_b128 v[134:137], v111 offset:32768
	ds_read_b128 v[138:141], v111 offset:34816
	ds_read_b128 v[142:145], v111 offset:36864
	ds_read_b128 v[146:149], v111 offset:38912
	s_waitcnt lgkmcnt(0)
	v_mfma_f32_16x16x32_bf16 v[62:65], v[134:137], v[116:119], v[62:65]
	v_mfma_f32_16x16x32_bf16 v[66:69], v[138:141], v[116:119], v[66:69]
	v_mfma_f32_16x16x32_bf16 v[70:73], v[142:145], v[116:119], v[70:73]
	v_mfma_f32_16x16x32_bf16 v[28:31], v[146:149], v[116:119], v[30:33]
	v_mfma_f32_16x16x32_bf16 v[58:61], v[134:137], v[120:123], v[58:61]
	v_mfma_f32_16x16x32_bf16 v[116:119], v[138:141], v[120:123], v[74:77]
	v_mfma_f32_16x16x32_bf16 v[150:153], v[142:145], v[120:123], v[78:81]
	v_mfma_f32_16x16x32_bf16 v[32:35], v[146:149], v[120:123], v[34:37]
	v_mfma_f32_16x16x32_bf16 v[120:123], v[134:137], v[124:127], v[82:85]
	v_mfma_f32_16x16x32_bf16 v[154:157], v[138:141], v[124:127], v[86:89]
	v_mfma_f32_16x16x32_bf16 v[112:115], v[142:145], v[124:127], v[112:115]
	v_mfma_f32_16x16x32_bf16 v[36:39], v[146:149], v[124:127], v[38:41]
	v_mfma_f32_16x16x32_bf16 v[124:127], v[134:137], v[130:133], v[46:49]
	v_mfma_f32_16x16x32_bf16 v[134:137], v[138:141], v[130:133], v[50:53]
	v_mfma_f32_16x16x32_bf16 v[138:141], v[142:145], v[130:133], v[54:57]
	v_mfma_f32_16x16x32_bf16 v[130:133], v[146:149], v[130:133], v[42:45]
	s_nop 2
	ds_read_b128 v[40:43], v109
	ds_read_b128 v[44:47], v109 offset:2048
	ds_read_b128 v[142:145], v109 offset:4096
	ds_read_b128 v[146:149], v109 offset:6144
	ds_read_b128 v[160:163], v108 offset:32768
	ds_read_b128 v[164:167], v108 offset:34816
	ds_read_b128 v[168:171], v108 offset:36864
	ds_read_b128 v[172:175], v108 offset:38912
	s_waitcnt vmcnt(0)
	s_waitcnt vmcnt(0) lgkmcnt(0)
	v_mfma_f32_16x16x32_bf16 v[48:51], v[168:171], v[142:145], v[112:115]
	s_barrier
	s_nop 1
	v_cndmask_b32_e64 v112, v0, v15, s[54:55]
	v_sub_u32_e32 v0, s74, v95
	v_mfma_f32_16x16x32_bf16 v[84:87], v[164:167], v[40:43], v[66:69]
	v_cndmask_b32_e64 v95, v1, v0, s[54:55]
	v_mfma_f32_16x16x32_bf16 v[80:83], v[168:171], v[40:43], v[70:73]
	v_mfma_f32_16x16x32_bf16 v[68:71], v[164:167], v[44:47], v[116:119]
	ds_read_b128 v[0:3], v110 offset:16384
	ds_read_b128 v[4:7], v110 offset:18432
	ds_read_b128 v[8:11], v110 offset:20480
	ds_read_b128 v[12:15], v110 offset:22528
	ds_read_b128 v[16:19], v111 offset:49152
	ds_read_b128 v[20:23], v111 offset:51200
	ds_read_b128 v[24:27], v111 offset:53248
	ds_read_b128 v[114:117], v111 offset:55296
	v_mfma_f32_16x16x32_bf16 v[88:91], v[160:163], v[40:43], v[62:65]
	v_mfma_f32_16x16x32_bf16 v[76:79], v[172:175], v[40:43], v[28:31]
	v_mfma_f32_16x16x32_bf16 v[72:75], v[160:163], v[44:47], v[58:61]
	v_mfma_f32_16x16x32_bf16 v[64:67], v[168:171], v[44:47], v[150:153]
	v_mfma_f32_16x16x32_bf16 v[60:63], v[172:175], v[44:47], v[32:35]
	v_mfma_f32_16x16x32_bf16 v[56:59], v[160:163], v[142:145], v[120:123]
	v_mfma_f32_16x16x32_bf16 v[52:55], v[164:167], v[142:145], v[154:157]
	v_mfma_f32_16x16x32_bf16 v[44:47], v[172:175], v[142:145], v[36:39]
	v_mfma_f32_16x16x32_bf16 v[40:43], v[160:163], v[146:149], v[124:127]
	v_mfma_f32_16x16x32_bf16 v[36:39], v[164:167], v[146:149], v[134:137]
	v_mfma_f32_16x16x32_bf16 v[28:31], v[168:171], v[146:149], v[138:141]
	v_mfma_f32_16x16x32_bf16 v[32:35], v[172:175], v[146:149], v[130:133]
	s_waitcnt lgkmcnt(3)
	v_mfma_f32_16x16x32_bf16 v[88:91], v[16:19], v[0:3], v[88:91]
	s_waitcnt lgkmcnt(2)
	v_mfma_f32_16x16x32_bf16 v[84:87], v[20:23], v[0:3], v[84:87]
	s_waitcnt lgkmcnt(1)
	v_mfma_f32_16x16x32_bf16 v[80:83], v[24:27], v[0:3], v[80:83]
	s_waitcnt lgkmcnt(0)
	v_mfma_f32_16x16x32_bf16 v[0:3], v[114:117], v[0:3], v[76:79]
	v_mfma_f32_16x16x32_bf16 v[72:75], v[16:19], v[4:7], v[72:75]
	v_mfma_f32_16x16x32_bf16 v[68:71], v[20:23], v[4:7], v[68:71]
	v_mfma_f32_16x16x32_bf16 v[64:67], v[24:27], v[4:7], v[64:67]
	v_mfma_f32_16x16x32_bf16 v[4:7], v[114:117], v[4:7], v[60:63]
	v_mfma_f32_16x16x32_bf16 v[76:79], v[16:19], v[8:11], v[56:59]
	v_mfma_f32_16x16x32_bf16 v[118:121], v[20:23], v[8:11], v[52:55]
	v_mfma_f32_16x16x32_bf16 v[122:125], v[24:27], v[8:11], v[48:51]
	v_mfma_f32_16x16x32_bf16 v[8:11], v[114:117], v[8:11], v[44:47]
	v_mfma_f32_16x16x32_bf16 v[130:133], v[16:19], v[12:15], v[40:43]
	v_mfma_f32_16x16x32_bf16 v[134:137], v[20:23], v[12:15], v[36:39]
	v_mfma_f32_16x16x32_bf16 v[138:141], v[24:27], v[12:15], v[28:31]
	v_mfma_f32_16x16x32_bf16 v[12:15], v[114:117], v[12:15], v[32:35]
	ds_read_b128 v[16:19], v109 offset:16384
	ds_read_b128 v[20:23], v109 offset:18432
	ds_read_b128 v[28:31], v109 offset:20480
	ds_read_b128 v[114:117], v109 offset:22528
	ds_read_b128 v[142:145], v108 offset:49152
	ds_read_b128 v[146:149], v108 offset:51200
	ds_read_b128 v[150:153], v108 offset:53248
	ds_read_b128 v[106:109], v108 offset:55296
	s_waitcnt lgkmcnt(3)
	v_mfma_f32_16x16x32_bf16 v[60:63], v[142:145], v[16:19], v[88:91]
	s_waitcnt lgkmcnt(2)
	v_mfma_f32_16x16x32_bf16 v[56:59], v[146:149], v[16:19], v[84:87]
	s_waitcnt lgkmcnt(1)
	v_mfma_f32_16x16x32_bf16 v[52:55], v[150:153], v[16:19], v[80:83]
	s_waitcnt lgkmcnt(0)
	v_mfma_f32_16x16x32_bf16 v[48:51], v[106:109], v[16:19], v[0:3]
	v_mfma_f32_16x16x32_bf16 v[32:35], v[142:145], v[20:23], v[72:75]
	v_mfma_f32_16x16x32_bf16 v[36:39], v[146:149], v[20:23], v[68:71]
	v_mfma_f32_16x16x32_bf16 v[40:43], v[150:153], v[20:23], v[64:67]
	v_mfma_f32_16x16x32_bf16 v[44:47], v[106:109], v[20:23], v[4:7]
	s_nop 1
	v_lshl_add_u32 v67, v95, 7, v158
	v_lshlrev_b32_e32 v66, 14, v92
	v_lshl_add_u64 v[64:65], v[98:99], 0, s[70:71]
	v_mfma_f32_16x16x32_bf16 v[16:19], v[142:145], v[28:31], v[76:79]
	v_cmp_lt_i32_e32 vcc, v67, v112
	v_mfma_f32_16x16x32_bf16 v[20:23], v[146:149], v[28:31], v[118:121]
	v_mfma_f32_16x16x32_bf16 v[24:27], v[150:153], v[28:31], v[122:125]
	v_mfma_f32_16x16x32_bf16 v[28:31], v[106:109], v[28:31], v[8:11]
	v_mfma_f32_16x16x32_bf16 v[0:3], v[142:145], v[114:117], v[130:133]
	v_mfma_f32_16x16x32_bf16 v[4:7], v[146:149], v[114:117], v[134:137]
	v_mfma_f32_16x16x32_bf16 v[8:11], v[150:153], v[114:117], v[138:141]
	v_mfma_f32_16x16x32_bf16 v[12:15], v[106:109], v[114:117], v[12:15]
	v_readlane_b32 s2, v242, 54
	v_readlane_b32 s3, v242, 55
	v_add_u32_e32 v251, -1, v112
	v_or_b32_e32 v243, 0, v67
	v_min_i32_e32 v243, v243, v251
	v_add_u32_e32 v243, v243, v66
	v_lshlrev_b32_e32 v243, 2, v243
	v_or_b32_e32 v244, 16, v67
	v_min_i32_e32 v244, v244, v251
	v_add_u32_e32 v244, v244, v66
	v_lshlrev_b32_e32 v244, 2, v244
	v_or_b32_e32 v245, 32, v67
	v_min_i32_e32 v245, v245, v251
	v_add_u32_e32 v245, v245, v66
	v_lshlrev_b32_e32 v245, 2, v245
	v_or_b32_e32 v246, 48, v67
	v_min_i32_e32 v246, v246, v251
	v_add_u32_e32 v246, v246, v66
	v_lshlrev_b32_e32 v246, 2, v246
	global_load_dword v243, v243, s[2:3]
	global_load_dword v244, v244, s[2:3]
	global_load_dword v245, v245, s[2:3]
	global_load_dword v246, v246, s[2:3]
	v_readlane_b32 s2, v242, 58
	v_readlane_b32 s3, v242, 59
	s_waitcnt vmcnt(0)
	v_lshlrev_b32_e32 v247, 2, v243
	v_lshlrev_b32_e32 v248, 2, v244
	v_lshlrev_b32_e32 v249, 2, v245
	v_lshlrev_b32_e32 v250, 2, v246
	s_nop 1
	global_load_dword v247, v247, s[2:3]
	global_load_dword v248, v248, s[2:3]
	global_load_dword v249, v249, s[2:3]
	global_load_dword v250, v250, s[2:3]
	s_waitcnt vmcnt(0)
	s_and_saveexec_b64 s[0:1], vcc
	s_cbranch_execz .LBB0_961
	v_add_u32_e32 v68, v67, v66
	v_readlane_b32 s2, v242, 54
	v_ashrrev_i32_e32 v69, 31, v68
	v_readlane_b32 s3, v242, 55
	s_nop 1
	v_lshl_add_u64 v[68:69], v[68:69], 2, s[2:3]
	v_mov_b32_e32 v68, v243
	v_readlane_b32 s2, v242, 58
	v_readlane_b32 s3, v242, 59
	s_waitcnt vmcnt(0)
	v_ashrrev_i32_e32 v69, 31, v68
	v_lshl_add_u64 v[70:71], v[68:69], 2, s[2:3]
	v_mov_b32_e32 v70, v247
	v_lshlrev_b64 v[68:69], 12, v[68:69]
	v_lshl_add_u64 v[68:69], v[64:65], 0, v[68:69]
	s_waitcnt vmcnt(0)
	v_pk_mul_f32 v[60:61], v[60:61], v[70:71] op_sel_hi:[1,0]
	v_pk_mul_f32 v[62:63], v[62:63], v[70:71] op_sel_hi:[1,0]
	v_pk_mul_f32 v[56:57], v[56:57], v[70:71] op_sel_hi:[1,0]
	v_pk_mul_f32 v[58:59], v[58:59], v[70:71] op_sel_hi:[1,0]
	v_pk_mul_f32 v[52:53], v[52:53], v[70:71] op_sel_hi:[1,0]
	v_pk_mul_f32 v[54:55], v[54:55], v[70:71] op_sel_hi:[1,0]
	v_pk_mul_f32 v[48:49], v[48:49], v[70:71] op_sel_hi:[1,0]
	v_pk_mul_f32 v[50:51], v[50:51], v[70:71] op_sel_hi:[1,0]
	v_cvt_pk_bf16_f32 v60, v60, v61
	v_cvt_pk_bf16_f32 v61, v62, v63
	v_cvt_pk_bf16_f32 v56, v56, v57
	v_cvt_pk_bf16_f32 v57, v58, v59
	v_cvt_pk_bf16_f32 v52, v52, v53
	v_cvt_pk_bf16_f32 v53, v54, v55
	v_cvt_pk_bf16_f32 v48, v48, v49
	v_cvt_pk_bf16_f32 v49, v50, v51
	global_store_dwordx2 v[68:69], v[60:61], off
	global_store_dwordx2 v[68:69], v[56:57], off offset:32
	global_store_dwordx2 v[68:69], v[52:53], off offset:64
	global_store_dwordx2 v[68:69], v[48:49], off offset:96
.LBB0_961:
	s_or_b64 exec, exec, s[0:1]
	v_or_b32_e32 v48, 16, v67
	v_cmp_lt_i32_e32 vcc, v48, v112
	s_and_saveexec_b64 s[0:1], vcc
	s_cbranch_execz .LBB0_963
	v_add_u32_e32 v48, v48, v66
	v_readlane_b32 s2, v242, 54
	v_ashrrev_i32_e32 v49, 31, v48
	v_readlane_b32 s3, v242, 55
	s_nop 1
	v_lshl_add_u64 v[48:49], v[48:49], 2, s[2:3]
	v_mov_b32_e32 v48, v244
	v_readlane_b32 s2, v242, 58
	v_readlane_b32 s3, v242, 59
	s_waitcnt vmcnt(0)
	v_ashrrev_i32_e32 v49, 31, v48
	v_lshl_add_u64 v[50:51], v[48:49], 2, s[2:3]
	v_mov_b32_e32 v50, v248
	v_lshlrev_b64 v[48:49], 12, v[48:49]
	v_lshl_add_u64 v[48:49], v[64:65], 0, v[48:49]
	s_waitcnt vmcnt(0)
	v_pk_mul_f32 v[32:33], v[32:33], v[50:51] op_sel_hi:[1,0]
	v_pk_mul_f32 v[34:35], v[34:35], v[50:51] op_sel_hi:[1,0]
	v_pk_mul_f32 v[36:37], v[36:37], v[50:51] op_sel_hi:[1,0]
	v_pk_mul_f32 v[38:39], v[38:39], v[50:51] op_sel_hi:[1,0]
	v_pk_mul_f32 v[40:41], v[40:41], v[50:51] op_sel_hi:[1,0]
	v_pk_mul_f32 v[42:43], v[42:43], v[50:51] op_sel_hi:[1,0]
	v_pk_mul_f32 v[44:45], v[44:45], v[50:51] op_sel_hi:[1,0]
	v_pk_mul_f32 v[46:47], v[46:47], v[50:51] op_sel_hi:[1,0]
	v_cvt_pk_bf16_f32 v32, v32, v33
	v_cvt_pk_bf16_f32 v33, v34, v35
	v_cvt_pk_bf16_f32 v34, v36, v37
	v_cvt_pk_bf16_f32 v35, v38, v39
	v_cvt_pk_bf16_f32 v36, v40, v41
	v_cvt_pk_bf16_f32 v37, v42, v43
	v_cvt_pk_bf16_f32 v38, v44, v45
	v_cvt_pk_bf16_f32 v39, v46, v47
	global_store_dwordx2 v[48:49], v[32:33], off
	global_store_dwordx2 v[48:49], v[34:35], off offset:32
	global_store_dwordx2 v[48:49], v[36:37], off offset:64
	global_store_dwordx2 v[48:49], v[38:39], off offset:96
.LBB0_963:
	s_or_b64 exec, exec, s[0:1]
	v_or_b32_e32 v32, 32, v67
	v_cmp_lt_i32_e32 vcc, v32, v112
	s_and_saveexec_b64 s[0:1], vcc
	v_readlane_b32 s64, v242, 62
	v_readlane_b32 s96, v242, 60
	v_readlane_b32 s65, v242, 63
	v_readlane_b32 s97, v242, 61
	s_cbranch_execz .LBB0_965
	v_add_u32_e32 v32, v32, v66
	v_readlane_b32 s2, v242, 54
	v_ashrrev_i32_e32 v33, 31, v32
	v_readlane_b32 s3, v242, 55
	s_nop 1
	v_lshl_add_u64 v[32:33], v[32:33], 2, s[2:3]
	v_mov_b32_e32 v32, v245
	v_readlane_b32 s2, v242, 58
	v_readlane_b32 s3, v242, 59
	s_waitcnt vmcnt(0)
	v_ashrrev_i32_e32 v33, 31, v32
	v_lshl_add_u64 v[34:35], v[32:33], 2, s[2:3]
	v_mov_b32_e32 v34, v249
	v_lshlrev_b64 v[32:33], 12, v[32:33]
	v_lshl_add_u64 v[32:33], v[64:65], 0, v[32:33]
	s_waitcnt vmcnt(0)
	v_pk_mul_f32 v[16:17], v[16:17], v[34:35] op_sel_hi:[1,0]
	v_pk_mul_f32 v[18:19], v[18:19], v[34:35] op_sel_hi:[1,0]
	v_pk_mul_f32 v[20:21], v[20:21], v[34:35] op_sel_hi:[1,0]
	v_pk_mul_f32 v[22:23], v[22:23], v[34:35] op_sel_hi:[1,0]
	v_pk_mul_f32 v[24:25], v[24:25], v[34:35] op_sel_hi:[1,0]
	v_pk_mul_f32 v[26:27], v[26:27], v[34:35] op_sel_hi:[1,0]
	v_pk_mul_f32 v[28:29], v[28:29], v[34:35] op_sel_hi:[1,0]
	v_pk_mul_f32 v[30:31], v[30:31], v[34:35] op_sel_hi:[1,0]
	v_cvt_pk_bf16_f32 v16, v16, v17
	v_cvt_pk_bf16_f32 v17, v18, v19
	v_cvt_pk_bf16_f32 v18, v20, v21
	v_cvt_pk_bf16_f32 v19, v22, v23
	v_cvt_pk_bf16_f32 v20, v24, v25
	v_cvt_pk_bf16_f32 v21, v26, v27
	v_cvt_pk_bf16_f32 v22, v28, v29
	v_cvt_pk_bf16_f32 v23, v30, v31
	global_store_dwordx2 v[32:33], v[16:17], off
	global_store_dwordx2 v[32:33], v[18:19], off offset:32
	global_store_dwordx2 v[32:33], v[20:21], off offset:64
	global_store_dwordx2 v[32:33], v[22:23], off offset:96
.LBB0_965:
	s_or_b64 exec, exec, s[0:1]
	v_or_b32_e32 v16, 48, v67
	v_cmp_lt_i32_e32 vcc, v16, v112
	s_and_saveexec_b64 s[0:1], vcc
	s_cbranch_execz .LBB0_958
	v_add_u32_e32 v16, v16, v66
	v_readlane_b32 s2, v242, 54
	v_ashrrev_i32_e32 v17, 31, v16
	v_readlane_b32 s3, v242, 55
	s_nop 1
	v_lshl_add_u64 v[16:17], v[16:17], 2, s[2:3]
	v_mov_b32_e32 v16, v246
	v_readlane_b32 s2, v242, 58
	v_readlane_b32 s3, v242, 59
	s_waitcnt vmcnt(0)
	v_ashrrev_i32_e32 v17, 31, v16
	v_lshl_add_u64 v[18:19], v[16:17], 2, s[2:3]
	v_mov_b32_e32 v18, v250
	v_lshlrev_b64 v[16:17], 12, v[16:17]
	v_lshl_add_u64 v[16:17], v[64:65], 0, v[16:17]
	s_waitcnt vmcnt(0)
	v_pk_mul_f32 v[0:1], v[0:1], v[18:19] op_sel_hi:[1,0]
	v_pk_mul_f32 v[2:3], v[2:3], v[18:19] op_sel_hi:[1,0]
	v_pk_mul_f32 v[4:5], v[4:5], v[18:19] op_sel_hi:[1,0]
	v_pk_mul_f32 v[6:7], v[6:7], v[18:19] op_sel_hi:[1,0]
	v_pk_mul_f32 v[8:9], v[8:9], v[18:19] op_sel_hi:[1,0]
	v_pk_mul_f32 v[10:11], v[10:11], v[18:19] op_sel_hi:[1,0]
	v_pk_mul_f32 v[12:13], v[12:13], v[18:19] op_sel_hi:[1,0]
	v_pk_mul_f32 v[14:15], v[14:15], v[18:19] op_sel_hi:[1,0]
	v_cvt_pk_bf16_f32 v0, v0, v1
	v_cvt_pk_bf16_f32 v1, v2, v3
	v_cvt_pk_bf16_f32 v2, v4, v5
	v_cvt_pk_bf16_f32 v3, v6, v7
	v_cvt_pk_bf16_f32 v4, v8, v9
	v_cvt_pk_bf16_f32 v5, v10, v11
	v_cvt_pk_bf16_f32 v6, v12, v13
	v_cvt_pk_bf16_f32 v7, v14, v15
	global_store_dwordx2 v[16:17], v[0:1], off
	global_store_dwordx2 v[16:17], v[2:3], off offset:32
	global_store_dwordx2 v[16:17], v[4:5], off offset:64
	global_store_dwordx2 v[16:17], v[6:7], off offset:96
	s_branch .LBB0_958
